# MLA loop VALU trimming: strength-reduced prefetch addresses (per-lane base+stride, uniform row in SGPR), cross-lane max deferred to rare rescale path, persistent -mref / ones registers
# speedup vs baseline: 1.0643x; 1.0110x over previous
.LBB0_1370:
	v_exp_f32_e32 v96, v96
	v_exp_f32_e32 v97, v97
	v_exp_f32_e32 v98, v98
	v_exp_f32_e32 v99, v99
	v_exp_f32_e32 v100, v100
	v_exp_f32_e32 v101, v101
	v_exp_f32_e32 v102, v102
	v_exp_f32_e32 v103, v103
	v_cvt_pk_bf16_f32 v96, v96, v97
	v_cvt_pk_bf16_f32 v97, v98, v99
	v_cvt_pk_bf16_f32 v98, v100, v101
	v_cvt_pk_bf16_f32 v99, v102, v103
	v_exp_f32_e32 v88, v88
	v_exp_f32_e32 v89, v89
	v_exp_f32_e32 v90, v90
	v_exp_f32_e32 v91, v91
	v_exp_f32_e32 v100, v92
	v_exp_f32_e32 v101, v93
	v_exp_f32_e32 v102, v94
	v_exp_f32_e32 v103, v95
	v_mov_b64_e32 v[136:137], s[14:15]
	v_mov_b64_e32 v[134:135], s[12:13]
	v_mov_b32_e32 v109, v108
	v_mov_b32_e32 v110, v108
	v_mov_b32_e32 v111, v108
	s_waitcnt lgkmcnt(1)
	v_mov_b32_e32 v105, v104
	v_mov_b32_e32 v106, v104
	s_waitcnt lgkmcnt(0)
	v_mov_b32_e32 v107, v104
	v_cvt_pk_bf16_f32 v88, v88, v89
	v_cvt_pk_bf16_f32 v89, v90, v91
	v_cvt_pk_bf16_f32 v90, v100, v101
	v_cvt_pk_bf16_f32 v91, v102, v103
	v_mfma_f32_16x16x32_bf16 v[100:103], v[68:71], v[96:99], v[108:111]
	v_exp_f32_e32 v113, v76
	v_exp_f32_e32 v115, v81
	v_exp_f32_e32 v117, v82
	v_mfma_f32_16x16x32_bf16 v[122:125], v[68:71], v[88:91], v[104:107]
	v_exp_f32_e32 v68, v77
	v_exp_f32_e32 v69, v78
	v_exp_f32_e32 v70, v79
	v_mfma_f32_16x16x32_bf16 v[76:79], v[64:67], v[96:99], v[108:111]
	v_exp_f32_e32 v71, v80
	v_cvt_pk_bf16_f32 v80, v113, v68
	v_cvt_pk_bf16_f32 v81, v69, v70
	v_mfma_f32_16x16x32_bf16 v[126:129], v[64:67], v[88:91], v[104:107]
	v_exp_f32_e32 v64, v83
	v_cvt_pk_bf16_f32 v82, v71, v115
	s_waitcnt vmcnt(1)
	ds_write_b128 v121, v[32:35] offset:13312
	v_mfma_f32_16x16x32_bf16 v[130:133], v[52:55], v[96:99], v[108:111]
	v_cvt_pk_bf16_f32 v83, v117, v64
	v_lshlrev_b32_e32 v144, 1, v116
	v_mfma_f32_16x16x32_bf16 v[138:141], v[52:55], v[88:91], v[104:107]
	v_exp_f32_e32 v52, v56
	v_exp_f32_e32 v53, v57
	v_exp_f32_e32 v54, v58
	v_exp_f32_e32 v55, v59
	v_exp_f32_e32 v56, v60
	v_exp_f32_e32 v57, v61
	v_exp_f32_e32 v58, v62
	v_exp_f32_e32 v59, v63
	v_mfma_f32_16x16x32_bf16 v[92:95], v[84:87], v[96:99], v[108:111]
	v_mfma_f32_16x16x32_bf16 v[84:87], v[84:87], v[88:91], v[104:107]
	v_mfma_f32_16x16x32_bf16 v[96:99], v[134:137], v[96:99], v[108:111]
	v_mfma_f32_16x16x32_bf16 v[88:91], v[134:137], v[88:91], v[104:107]
	s_nop 2
	v_cvt_pk_bf16_f32 v104, v52, v53
	v_cvt_pk_bf16_f32 v105, v54, v55
	v_cvt_pk_bf16_f32 v106, v56, v57
	v_cvt_pk_bf16_f32 v107, v58, v59
	v_mfma_f32_16x16x32_bf16 v[68:71], v[48:51], v[80:83], v[92:95]
	s_nop 0
	v_mfma_f32_16x16x32_bf16 v[64:67], v[48:51], v[104:107], v[84:87]
	v_mfma_f32_16x16x32_bf16 v[60:63], v[44:47], v[80:83], v[100:103]
	v_mfma_f32_16x16x32_bf16 v[56:59], v[44:47], v[104:107], v[122:125]
	v_mfma_f32_16x16x32_bf16 v[52:55], v[40:43], v[80:83], v[76:79]
	v_mfma_f32_16x16x32_bf16 v[48:51], v[40:43], v[104:107], v[126:129]
	v_mfma_f32_16x16x32_bf16 v[44:47], v[36:39], v[80:83], v[130:133]
	v_mfma_f32_16x16x32_bf16 v[40:43], v[36:39], v[104:107], v[138:141]
	v_mfma_f32_16x16x32_bf16 v[36:39], v[134:137], v[80:83], v[96:99]
	v_mfma_f32_16x16x32_bf16 v[32:35], v[134:137], v[104:107], v[88:91]
	s_and_saveexec_b64 s[26:27], s[6:7]
	v_lshl_add_u32 v76, v171, 1, v144
	ds_write_b128 v76, v[28:31] offset:13312
	s_or_b64 exec, exec, s[26:27]
	s_lshl_b32 s26, s43, 8
	v_mov_b32_e32 v115, v145
	s_addk_i32 s26, 0x7800
	s_mov_b32 s27, 1
	v_lshl_add_u64 v[160:161], s[0:1], 0, v[114:115]
	v_add_u32_e32 v177, 0x80, v119
	v_add_u32_e32 v178, 0x80, v120
	v_add_u32_e32 v179, 0x80, v118
	v_lshlrev_b32_e32 v180, 1, v112
	v_mov_b32_e32 v203, 0
	v_mov_b32_e32 v210, v179
	v_mov_b32_e32 v211, 0
	v_mov_b32_e32 v214, 0x800
	v_lshlrev_b64 v[212:213], 11, v[210:211]
	v_lshlrev_b64 v[210:211], 6, v[210:211]
	v_lshl_add_u64 v[210:211], v[152:153], 0, v[210:211]
	v_lshl_add_u64 v[212:213], v[150:151], 0, v[212:213]
	v_lshl_add_u64 v[210:211], v[210:211], 0, s[24:25]
	v_cndmask_b32_e64 v205, v211, v213, s[4:5]
	v_cndmask_b32_e64 v204, v210, v212, s[4:5]
	v_mov_b32_e32 v206, 64
	v_cndmask_b32_e64 v206, v206, v214, s[4:5]
	v_mov_b32_e32 v210, v177
	v_mov_b32_e32 v211, 0
	v_lshlrev_b64 v[212:213], 11, v[210:211]
	v_lshlrev_b64 v[210:211], 6, v[210:211]
	v_lshl_add_u64 v[212:213], v[156:157], 0, v[212:213]
	v_lshl_add_u64 v[210:211], v[154:155], 0, v[210:211]
	v_cndmask_b32_e64 v209, v211, v213, s[8:9]
	v_cndmask_b32_e64 v208, v210, v212, s[8:9]
	v_mov_b32_e32 v207, 64
	v_cndmask_b32_e64 v207, v207, v214, s[8:9]
	v_mov_b32_e32 v210, v178
	v_mov_b32_e32 v211, 0
	v_lshlrev_b64 v[210:211], 11, v[210:211]
	v_lshl_add_u64 v[216:217], v[160:161], 0, v[210:211]
	v_xor_b32_e32 v218, 0x80000000, v159
	v_xor_b32_e32 v222, 0x80000000, v158
	v_mov_b32_e32 v219, v218
	v_mov_b32_e32 v220, v218
	v_mov_b32_e32 v221, v218
	v_mov_b32_e32 v223, v222
	v_mov_b32_e32 v224, v222
	v_mov_b32_e32 v225, v222
	v_mov_b64_e32 v[228:229], s[12:13]
	v_mov_b64_e32 v[230:231], s[14:15]
	s_waitcnt vmcnt(0)
	ds_write_b128 v174, v[72:75] offset:36864
	s_waitcnt lgkmcnt(0)
	s_barrier
	s_branch .LBB0_1374
.LBB0_1373:
	s_or_b64 exec, exec, s[0:1]
	s_add_i32 s27, s27, 1
	s_mulk_i32 s43, 0x2800
	v_add_u32_e32 v72, s43, v174
	s_cmp_lg_u32 s27, 35
	s_waitcnt vmcnt(0)
	ds_write_b128 v72, v[76:79] offset:26624
	s_waitcnt lgkmcnt(0)
	s_barrier
	s_cbranch_scc0 .LBB0_1380
.LBB0_1374:
	s_cmp_lt_u32 s27, 31
	s_cselect_b32 s43, s42, s26
	s_lshl_b32 s98, s27, 6
	s_add_i32 s98, s98, s43
	s_addk_i32 s98, 0xffc0
	s_lshl_b32 s100, s98, 11
	s_mov_b32 s101, 0
	v_mul_u32_u24_e32 v202, s98, v206
	v_lshl_add_u64 v[72:73], v[204:205], 0, v[202:203]
	global_load_dwordx4 v[72:75], v[72:73], off
	s_and_saveexec_b64 s[0:1], s[6:7]
	s_cbranch_execz .LBB0_1376
	v_mul_u32_u24_e32 v202, s98, v207
	v_lshl_add_u64 v[28:29], v[208:209], 0, v[202:203]
	global_load_dwordx4 v[28:31], v[28:29], off
.LBB0_1376:
	s_or_b64 exec, exec, s[0:1]
	s_and_b32 s0, s27, 1
	s_mul_i32 s1, s0, 0x3400
	v_add_u32_e32 v124, s1, v175
	ds_read_b128 v[76:79], v124
	ds_read_b128 v[88:91], v124 offset:64
	s_waitcnt lgkmcnt(1)
	v_mfma_f32_16x16x32_bf16 v[92:95], v[76:79], v[20:23], v[218:221]
	ds_read_b128 v[96:99], v124 offset:3328
	ds_read_b128 v[100:103], v124 offset:128
	ds_read_b128 v[108:111], v124 offset:6656
	ds_read_b128 v[112:115], v124 offset:6720
	ds_read_b128 v[120:123], v124 offset:9984
	ds_read_b128 v[182:185], v124 offset:6784
	v_mfma_f32_16x16x32_bf16 v[76:79], v[76:79], v[24:27], v[222:225]
	s_mul_i32 s1, s0, 0x2800
	s_waitcnt lgkmcnt(5)
	v_mfma_f32_16x16x32_bf16 v[104:107], v[96:99], v[20:23], v[218:221]
	v_mfma_f32_16x16x32_bf16 v[96:99], v[96:99], v[24:27], v[222:225]
	s_waitcnt lgkmcnt(3)
	v_mfma_f32_16x16x32_bf16 v[116:119], v[108:111], v[20:23], v[218:221]
	v_mfma_f32_16x16x32_bf16 v[108:111], v[108:111], v[24:27], v[222:225]
	s_waitcnt lgkmcnt(1)
	v_mfma_f32_16x16x32_bf16 v[80:83], v[120:123], v[20:23], v[218:221]
	v_mfma_f32_16x16x32_bf16 v[84:87], v[120:123], v[24:27], v[222:225]
	v_mfma_f32_16x16x32_bf16 v[92:95], v[88:91], v[12:15], v[92:95]
	v_mfma_f32_16x16x32_bf16 v[76:79], v[88:91], v[16:19], v[76:79]
	ds_read_b128 v[88:91], v124 offset:3392
	ds_read_b128 v[120:123], v124 offset:3456
	s_waitcnt lgkmcnt(1)
	v_mfma_f32_16x16x32_bf16 v[104:107], v[88:91], v[12:15], v[104:107]
	v_mfma_f32_16x16x32_bf16 v[88:91], v[88:91], v[16:19], v[96:99]
	s_nop 2
	ds_read_b128 v[96:99], v124 offset:10048
	ds_read_b128 v[190:193], v124 offset:10112
	s_waitcnt lgkmcnt(1)
	v_mfma_f32_16x16x32_bf16 v[194:197], v[96:99], v[12:15], v[80:83]
	s_nop 2
	v_mfma_f32_16x16x32_bf16 v[128:131], v[100:103], v[4:7], v[76:79]
	v_add_u32_e32 v82, s1, v176
	s_nop 1
	v_lshl_add_u64 v[76:77], v[216:217], 0, s[100:101]
	global_load_dwordx4 v[76:79], v[76:77], off offset:128
	v_mfma_f32_16x16x32_bf16 v[116:119], v[112:115], v[12:15], v[116:119]
	v_mfma_f32_16x16x32_bf16 v[186:189], v[112:115], v[16:19], v[108:111]
	v_mfma_f32_16x16x32_bf16 v[198:201], v[96:99], v[16:19], v[84:87]
	ds_read_b64_tr_b16 v[124:125], v82 offset:26624
	ds_read_b64_tr_b16 v[112:113], v82 offset:26656
	ds_read_b64_tr_b16 v[108:109], v82 offset:26688
	ds_read_b64_tr_b16 v[96:97], v82 offset:26720
	ds_read_b64_tr_b16 v[126:127], v82 offset:29184
	ds_read_b64_tr_b16 v[114:115], v82 offset:29216
	ds_read_b64_tr_b16 v[110:111], v82 offset:29248
	ds_read_b64_tr_b16 v[98:99], v82 offset:29280
	v_mfma_f32_16x16x32_bf16 v[136:139], v[100:103], v[8:11], v[92:95]
	v_mfma_f32_16x16x32_bf16 v[132:135], v[120:123], v[4:7], v[88:91]
	s_nop 1
	ds_read_b64_tr_b16 v[92:93], v82 offset:31744
	ds_read_b64_tr_b16 v[88:89], v82 offset:31776
	ds_read_b64_tr_b16 v[84:85], v82 offset:31808
	ds_read_b64_tr_b16 v[80:81], v82 offset:31840
	ds_read_b64_tr_b16 v[94:95], v82 offset:34304
	ds_read_b64_tr_b16 v[90:91], v82 offset:34336
	ds_read_b64_tr_b16 v[86:87], v82 offset:34368
	ds_read_b64_tr_b16 v[82:83], v82 offset:34400
	v_mfma_f32_16x16x32_bf16 v[140:143], v[120:123], v[8:11], v[104:107]
	v_mfma_f32_16x16x32_bf16 v[116:119], v[182:185], v[8:11], v[116:119]
	v_mfma_f32_16x16x32_bf16 v[100:103], v[182:185], v[4:7], v[186:189]
	s_waitcnt lgkmcnt(14)
	v_mfma_f32_16x16x32_bf16 v[120:123], v[190:193], v[8:11], v[194:197]
	v_mfma_f32_16x16x32_bf16 v[104:107], v[190:193], v[4:7], v[198:201]
	v_max3_f32 v181, v136, v137, v138
	v_max3_f32 v183, v128, v129, v130
	v_max3_f32 v184, v131, v132, v133
	v_max3_f32 v181, v181, v139, v140
	v_max3_f32 v183, v183, v134, v135
	v_max3_f32 v181, v181, v141, v142
	v_max3_f32 v182, v143, v116, v117
	v_max3_f32 v184, v184, v100, v101
	v_max3_f32 v182, v182, v118, v119
	v_max3_f32 v184, v184, v102, v103
	v_max3_f32 v181, v181, v120, v121
	v_max3_f32 v182, v182, v122, v123
	v_max3_f32 v183, v183, v104, v105
	v_max3_f32 v184, v184, v106, v107
	v_max_f32_e32 v181, v181, v182
	v_max_f32_e32 v183, v183, v184
	v_max_f32_e32 v184, v181, v183
	v_cmp_lt_f32_e32 vcc, s36, v184
	s_cbranch_vccz .LBB0_1378
	v_mov_b32_e32 v182, v181
	v_mov_b32_e32 v184, v183
	s_nop 1
	v_permlane16_swap_b32_e32 v181, v182
	v_permlane16_swap_b32_e32 v183, v184
	v_max_f32_e32 v181, v181, v182
	v_max_f32_e32 v183, v183, v184
	v_mov_b32_e32 v182, v181
	v_mov_b32_e32 v184, v183
	s_nop 1
	v_permlane32_swap_b32_e32 v181, v182
	v_permlane32_swap_b32_e32 v183, v184
	v_max_f32_e32 v182, v181, v182
	v_max_f32_e32 v181, v183, v184
	v_max_f32_e32 v182, v182, v182
	v_max_f32_e32 v183, 0, v182
	v_exp_f32_e64 v182, -v183
	v_max_f32_e32 v181, v181, v181
	v_sub_f32_e32 v136, v136, v183
	v_sub_f32_e32 v137, v137, v183
	v_pk_mul_f32 v[70:71], v[70:71], v[182:183] op_sel_hi:[1,0]
	v_pk_mul_f32 v[68:69], v[68:69], v[182:183] op_sel_hi:[1,0]
	v_pk_mul_f32 v[62:63], v[62:63], v[182:183] op_sel_hi:[1,0]
	v_pk_mul_f32 v[60:61], v[60:61], v[182:183] op_sel_hi:[1,0]
	v_pk_mul_f32 v[54:55], v[54:55], v[182:183] op_sel_hi:[1,0]
	v_pk_mul_f32 v[52:53], v[52:53], v[182:183] op_sel_hi:[1,0]
	v_pk_mul_f32 v[46:47], v[46:47], v[182:183] op_sel_hi:[1,0]
	v_pk_mul_f32 v[44:45], v[44:45], v[182:183] op_sel_hi:[1,0]
	v_pk_mul_f32 v[38:39], v[38:39], v[182:183] op_sel_hi:[1,0]
	v_pk_mul_f32 v[36:37], v[36:37], v[182:183] op_sel_hi:[1,0]
	v_max_f32_e32 v182, 0, v181
	v_exp_f32_e64 v184, -v182
	v_sub_f32_e32 v138, v138, v183
	v_sub_f32_e32 v139, v139, v183
	v_sub_f32_e32 v140, v140, v183
	v_sub_f32_e32 v141, v141, v183
	v_sub_f32_e32 v142, v142, v183
	v_sub_f32_e32 v143, v143, v183
	v_sub_f32_e32 v116, v116, v183
	v_sub_f32_e32 v117, v117, v183
	v_sub_f32_e32 v118, v118, v183
	v_sub_f32_e32 v119, v119, v183
	v_sub_f32_e32 v120, v120, v183
	v_sub_f32_e32 v121, v121, v183
	v_sub_f32_e32 v122, v122, v183
	v_sub_f32_e32 v123, v123, v183
	v_pk_add_f32 v[158:159], v[158:159], v[182:183]
	v_xor_b32_e32 v218, 0x80000000, v159
	v_xor_b32_e32 v222, 0x80000000, v158
	v_mov_b32_e32 v219, v218
	v_mov_b32_e32 v220, v218
	v_mov_b32_e32 v221, v218
	v_mov_b32_e32 v223, v222
	v_mov_b32_e32 v224, v222
	v_mov_b32_e32 v225, v222
	v_sub_f32_e32 v128, v128, v182
	v_sub_f32_e32 v129, v129, v182
	v_sub_f32_e32 v130, v130, v182
	v_sub_f32_e32 v131, v131, v182
	v_sub_f32_e32 v132, v132, v182
	v_sub_f32_e32 v133, v133, v182
	v_sub_f32_e32 v134, v134, v182
	v_sub_f32_e32 v135, v135, v182
	v_sub_f32_e32 v100, v100, v182
	v_sub_f32_e32 v101, v101, v182
	v_sub_f32_e32 v102, v102, v182
	v_sub_f32_e32 v103, v103, v182
	v_sub_f32_e32 v104, v104, v182
	v_sub_f32_e32 v105, v105, v182
	v_sub_f32_e32 v106, v106, v182
	v_sub_f32_e32 v107, v107, v182
	v_pk_mul_f32 v[66:67], v[66:67], v[184:185] op_sel_hi:[1,0]
	v_pk_mul_f32 v[64:65], v[64:65], v[184:185] op_sel_hi:[1,0]
	v_pk_mul_f32 v[58:59], v[58:59], v[184:185] op_sel_hi:[1,0]
	v_pk_mul_f32 v[56:57], v[56:57], v[184:185] op_sel_hi:[1,0]
	v_pk_mul_f32 v[50:51], v[50:51], v[184:185] op_sel_hi:[1,0]
	v_pk_mul_f32 v[48:49], v[48:49], v[184:185] op_sel_hi:[1,0]
	v_pk_mul_f32 v[42:43], v[42:43], v[184:185] op_sel_hi:[1,0]
	v_pk_mul_f32 v[40:41], v[40:41], v[184:185] op_sel_hi:[1,0]
	v_pk_mul_f32 v[34:35], v[34:35], v[184:185] op_sel_hi:[1,0]
	v_pk_mul_f32 v[32:33], v[32:33], v[184:185] op_sel_hi:[1,0]
.LBB0_1378:
	v_exp_f32_e32 v136, v136
	v_exp_f32_e32 v137, v137
	v_exp_f32_e32 v138, v138
	v_exp_f32_e32 v139, v139
	v_exp_f32_e32 v140, v140
	v_exp_f32_e32 v141, v141
	v_exp_f32_e32 v142, v142
	v_exp_f32_e32 v143, v143
	v_exp_f32_e32 v128, v128
	v_exp_f32_e32 v129, v129
	v_exp_f32_e32 v130, v130
	v_exp_f32_e32 v131, v131
	v_exp_f32_e32 v132, v132
	v_exp_f32_e32 v133, v133
	v_exp_f32_e32 v134, v134
	v_exp_f32_e32 v135, v135
	v_cvt_pk_bf16_f32 v136, v136, v137
	v_cvt_pk_bf16_f32 v137, v138, v139
	v_cvt_pk_bf16_f32 v138, v140, v141
	v_cvt_pk_bf16_f32 v139, v142, v143
	v_cvt_pk_bf16_f32 v128, v128, v129
	v_cvt_pk_bf16_f32 v129, v130, v131
	v_cvt_pk_bf16_f32 v130, v132, v133
	v_cvt_pk_bf16_f32 v131, v134, v135
	s_waitcnt lgkmcnt(0)
	v_mfma_f32_16x16x32_bf16 v[60:63], v[112:115], v[136:139], v[60:63]
	v_exp_f32_e32 v116, v116
	s_xor_b32 s43, s0, 1
	s_mul_i32 s46, s43, 0x3400
	v_mfma_f32_16x16x32_bf16 v[56:59], v[112:115], v[128:131], v[56:59]
	v_exp_f32_e32 v112, v117
	v_exp_f32_e32 v113, v118
	v_exp_f32_e32 v114, v119
	v_exp_f32_e32 v115, v120
	v_exp_f32_e32 v117, v121
	v_mfma_f32_16x16x32_bf16 v[52:55], v[108:111], v[136:139], v[52:55]
	v_exp_f32_e32 v118, v122
	v_mfma_f32_16x16x32_bf16 v[48:51], v[108:111], v[128:131], v[48:51]
	v_cvt_pk_bf16_f32 v108, v116, v112
	v_cvt_pk_bf16_f32 v109, v113, v114
	v_cvt_pk_bf16_f32 v110, v115, v117
	v_exp_f32_e32 v111, v123
	v_mfma_f32_16x16x32_bf16 v[44:47], v[96:99], v[136:139], v[44:47]
	v_cvt_pk_bf16_f32 v111, v118, v111
	v_mfma_f32_16x16x32_bf16 v[40:43], v[96:99], v[128:131], v[40:43]
	v_exp_f32_e32 v96, v100
	v_exp_f32_e32 v97, v101
	v_exp_f32_e32 v98, v102
	v_exp_f32_e32 v99, v103
	v_exp_f32_e32 v100, v104
	v_exp_f32_e32 v101, v105
	v_exp_f32_e32 v102, v106
	v_exp_f32_e32 v103, v107
	v_mfma_f32_16x16x32_bf16 v[68:71], v[124:127], v[136:139], v[68:71]
	v_cvt_pk_bf16_f32 v96, v96, v97
	v_cvt_pk_bf16_f32 v97, v98, v99
	v_cvt_pk_bf16_f32 v98, v100, v101
	v_mfma_f32_16x16x32_bf16 v[64:67], v[124:127], v[128:131], v[64:67]
	v_cvt_pk_bf16_f32 v99, v102, v103
	v_mfma_f32_16x16x32_bf16 v[36:39], v[228:231], v[136:139], v[36:39]
	v_mfma_f32_16x16x32_bf16 v[32:35], v[228:231], v[128:131], v[32:35]
	v_mfma_f32_16x16x32_bf16 v[68:71], v[92:95], v[108:111], v[68:71]
	v_mfma_f32_16x16x32_bf16 v[64:67], v[92:95], v[96:99], v[64:67]
	v_mfma_f32_16x16x32_bf16 v[60:63], v[88:91], v[108:111], v[60:63]
	v_mfma_f32_16x16x32_bf16 v[56:59], v[88:91], v[96:99], v[56:59]
	v_mfma_f32_16x16x32_bf16 v[52:55], v[84:87], v[108:111], v[52:55]
	v_mfma_f32_16x16x32_bf16 v[48:51], v[84:87], v[96:99], v[48:51]
	v_mfma_f32_16x16x32_bf16 v[44:47], v[80:83], v[108:111], v[44:47]
	v_mfma_f32_16x16x32_bf16 v[40:43], v[80:83], v[96:99], v[40:43]
	v_lshlrev_b32_e32 v80, 1, v170
	v_add3_u32 v80, s46, v80, v180
	s_waitcnt vmcnt(1)
	ds_write_b128 v80, v[72:75]
	v_mfma_f32_16x16x32_bf16 v[36:39], v[228:231], v[108:111], v[36:39]
	v_mfma_f32_16x16x32_bf16 v[32:35], v[228:231], v[96:99], v[32:35]
	s_and_saveexec_b64 s[0:1], s[6:7]
	s_cbranch_execz .LBB0_1373
	v_lshlrev_b32_e32 v72, 1, v171
	v_add3_u32 v72, s46, v72, v144
	ds_write_b128 v72, v[28:31]
	s_branch .LBB0_1373

	.amdhsa_kernel _Z14fwd_megakernel6Params
		.amdhsa_group_segment_fixed_size 158608
		.amdhsa_private_segment_fixed_size 0
		.amdhsa_kernarg_size 600
		.amdhsa_user_sgpr_count 2
		.amdhsa_user_sgpr_dispatch_ptr 0
		.amdhsa_user_sgpr_queue_ptr 0
		.amdhsa_user_sgpr_kernarg_segment_ptr 1
		.amdhsa_user_sgpr_dispatch_id 0
		.amdhsa_user_sgpr_kernarg_preload_length 0
		.amdhsa_user_sgpr_kernarg_preload_offset 0
		.amdhsa_user_sgpr_private_segment_size 0
		.amdhsa_uses_dynamic_stack 0
		.amdhsa_enable_private_segment 0
		.amdhsa_system_sgpr_workgroup_id_x 1
		.amdhsa_system_sgpr_workgroup_id_y 0
		.amdhsa_system_sgpr_workgroup_id_z 0
		.amdhsa_system_sgpr_workgroup_info 0
		.amdhsa_system_vgpr_workitem_id 2
		.amdhsa_next_free_vgpr 248
		.amdhsa_next_free_sgpr 102
		.amdhsa_accum_offset 248
		.amdhsa_reserve_vcc 1
		.amdhsa_float_round_mode_32 0
		.amdhsa_float_round_mode_16_64 0
		.amdhsa_float_denorm_mode_32 3
		.amdhsa_float_denorm_mode_16_64 3
		.amdhsa_dx10_clamp 1
		.amdhsa_ieee_mode 1
		.amdhsa_fp16_overflow 0
		.amdhsa_tg_split 0
		.amdhsa_exception_fp_ieee_invalid_op 0
		.amdhsa_exception_fp_denorm_src 0
		.amdhsa_exception_fp_ieee_div_zero 0
		.amdhsa_exception_fp_ieee_overflow 0
		.amdhsa_exception_fp_ieee_underflow 0
		.amdhsa_exception_fp_ieee_inexact 0
		.amdhsa_exception_int_div_zero 0
	.end_amdhsa_kernel

amdhsa.kernels:
  - .agpr_count:     0
    .args:
      - .offset:         0
        .size:           344
        .value_kind:     by_value
      - .offset:         344
        .size:           4
        .value_kind:     hidden_block_count_x
      - .offset:         348
        .size:           4
        .value_kind:     hidden_block_count_y
      - .offset:         352
        .size:           4
        .value_kind:     hidden_block_count_z
      - .offset:         356
        .size:           2
        .value_kind:     hidden_group_size_x
      - .offset:         358
        .size:           2
        .value_kind:     hidden_group_size_y
      - .offset:         360
        .size:           2
        .value_kind:     hidden_group_size_z
      - .offset:         362
        .size:           2
        .value_kind:     hidden_remainder_x
      - .offset:         364
        .size:           2
        .value_kind:     hidden_remainder_y
      - .offset:         366
        .size:           2
        .value_kind:     hidden_remainder_z
      - .offset:         384
        .size:           8
        .value_kind:     hidden_global_offset_x
      - .offset:         392
        .size:           8
        .value_kind:     hidden_global_offset_y
      - .offset:         400
        .size:           8
        .value_kind:     hidden_global_offset_z
      - .offset:         408
        .size:           2
        .value_kind:     hidden_grid_dims
      - .offset:         432
        .size:           8
        .value_kind:     hidden_multigrid_sync_arg
    .group_segment_fixed_size: 158608
    .kernarg_segment_align: 8
    .kernarg_segment_size: 600
    .language:       OpenCL C
    .language_version:
      - 2
      - 0
    .max_flat_workgroup_size: 512
    .name:           _Z14fwd_megakernel6Params
    .private_segment_fixed_size: 0
    .sgpr_count:     108
    .sgpr_spill_count: 86
    .symbol:         _Z14fwd_megakernel6Params.kd
    .uniform_work_group_size: 1
    .uses_dynamic_stack: false
    .vgpr_count:     248
    .vgpr_spill_count: 0
    .wavefront_size: 64
